# in-projection K-loop: LDS-DMA loads addressed as SGPR base + 32-bit lane offset, the 16 v_lshl_add_u64 per iteration removed
# baseline (speedup 1.0000x reference)
; #define PG8_STAGE(bufoff, gbase, voff) do { _Pragma("unroll") for (int _i = 0; _i < 2; ++_i) \
;         __builtin_amdgcn_global_load_lds((const unsigned*)((const char*)(gbase) + (voff)[_i]), (PG8_LAS unsigned*)(lds + (bufoff) + ldsw + _i * 8192), 16, 0, 0); } while (0)
; #define PG8_LDA(dst, b, h) do { _Pragma("unroll") for (int m = 0; m < 4; ++m) _Pragma("unroll") for (int k = 0; k < 2; ++k) dst[m][k] = *(const PG8_LAS bf16x8*)(lds + PG8_SA(b, h) + aoff + m * 2048 + k * 1024); } while (0)
; #define PG8_LDB(dst, b, h) do { _Pragma("unroll") for (int n = 0; n < 2; ++n) _Pragma("unroll") for (int k = 0; k < 2; ++k) dst[n][k] = *(const PG8_LAS bf16x8*)(lds + PG8_SB(b, h) + boff + n * 2048 + k * 1024); } while (0)
; #define PG8_MMA(ai, bj, At, Bt) do { __builtin_amdgcn_s_setprio(1); _Pragma("unroll") for (int m = 0; m < 4; ++m) _Pragma("unroll") for (int n = 0; n < 2; ++n) _Pragma("unroll") for (int k = 0; k < 2; ++k) \
;         acc[ai][bj][m][n] = __builtin_amdgcn_mfma_f32_16x16x32_bf16(Bt[n][k], At[m][k], acc[ai][bj][m][n], 0, 0, 0); __builtin_amdgcn_s_setprio(0); } while (0)
; #define PG8_WAIT_V(n) asm volatile("s_waitcnt vmcnt(" #n ")" ::: "memory")
; #define PG8_BAR __builtin_amdgcn_s_barrier()
; template <class Epi, class Sched, bool ALIGN_EPI = false, bool SP2 = false>
; __device__ __forceinline__ void gemm_phase(PG8_LAS unsigned char* lds, const Gemm g, const Sched& S, const Epi& E) {
;     ...
;         for (int t = 0; t < nt; t += 2) {
;             const bool last = (t == nt - 2);
;             const char* a1 = cA + (size_t)(t + 1) * kstep;
;             const char* a2 = last ? nA : cA + (size_t)(t + 2) * kstep; const char* b2 = last ? nB : cB + (size_t)(t + 2) * kstep;
;             const char* a3 = a2 + kstep; const char* b3 = b2 + kstep;
;             if (last && has_next) S.a_ready(nxt);
;             if constexpr (SP2) {
;             PG8_LDB(B0, 0, 0); PG8_LDB(B1, 0, 1); PG8_SCHED; PG8_LDA(At, 0, 0); PG8_STAGE(PG8_SA(1, 1), a1 + hstep, voffA);
;             PG8_WAIT_V(8); PG8_WAIT_L(0); PG8_BAR; PG8_MMA(0, 0, At, B0); PG8_MMA(0, 1, At, B1); PG8_BAR; PG8_SCHED;
;             PG8_LDA(At, 0, 1); PG8_STAGE(PG8_SB(0, 0), b2, voffB); PG8_STAGE(PG8_SB(0, 1), b2 + hstep, voffB); PG8_STAGE(PG8_SA(0, 0), a2, voffA);
;             PG8_WAIT_V(8); PG8_WAIT_L(0); PG8_BAR; PG8_MMA(1, 0, At, B0); PG8_MMA(1, 1, At, B1); PG8_BAR; PG8_SCHED;
.LBB0_133:
	s_add_u32 s18, s16, 0xfffc0080
	s_addc_u32 s19, s17, -1
	s_add_i32 s41, 0, 0x10000
	s_cmp_eq_u32 s40, 12
	s_cselect_b32 s21, s1, s19
	s_cselect_b32 s20, s11, s18
	v_add_u32_e32 v156, s41, v159
	s_cselect_b32 s19, s9, s39
	s_cselect_b32 s18, s33, s38
	s_add_i32 s44, 0, 0x14000
	ds_read_b128 v[144:147], v156
	ds_read_b128 v[148:151], v156 offset:1024
	ds_read_b128 v[152:155], v156 offset:2048
	ds_read_b128 v[162:165], v156 offset:3072
	v_add_u32_e32 v156, s44, v159
	ds_read_b128 v[166:169], v156
	ds_read_b128 v[170:173], v156 offset:1024
	ds_read_b128 v[174:177], v156 offset:2048
	ds_read_b128 v[178:181], v156 offset:3072
	s_add_i32 m0, s24, 0xc000
	ds_read_b128 v[182:185], v161
	ds_read_b128 v[194:197], v161 offset:1024
	ds_read_b128 v[198:201], v161 offset:2048
	ds_read_b128 v[202:205], v161 offset:3072
	ds_read_b128 v[210:213], v161 offset:4096
	ds_read_b128 v[214:217], v161 offset:5120
	ds_read_b128 v[218:221], v161 offset:6144
	ds_read_b128 v[222:225], v161 offset:7168
	global_load_lds_dwordx4 v140, s[16:17]
	s_add_i32 m0, s24, 0xe000
	s_nop 0
	global_load_lds_dwordx4 v142, s[16:17]
	s_waitcnt vmcnt(8)
	s_waitcnt lgkmcnt(0)
	s_barrier
	s_setprio 1
	s_waitcnt lgkmcnt(0)
	v_mfma_f32_16x16x32_bf16 v[124:127], v[144:147], v[182:185], v[124:127]
	v_mfma_f32_16x16x32_bf16 v[120:123], v[152:155], v[182:185], v[120:123]
	v_mfma_f32_16x16x32_bf16 v[108:111], v[144:147], v[198:201], v[108:111]
	v_mfma_f32_16x16x32_bf16 v[104:107], v[152:155], v[198:201], v[104:107]
	v_mfma_f32_16x16x32_bf16 v[92:95], v[144:147], v[210:213], v[92:95]
	v_mfma_f32_16x16x32_bf16 v[88:91], v[152:155], v[210:213], v[88:91]
	v_mfma_f32_16x16x32_bf16 v[76:79], v[144:147], v[218:221], v[76:79]
	v_mfma_f32_16x16x32_bf16 v[72:75], v[152:155], v[218:221], v[72:75]
	v_mfma_f32_16x16x32_bf16 v[124:127], v[148:151], v[194:197], v[124:127]
	v_mfma_f32_16x16x32_bf16 v[120:123], v[162:165], v[194:197], v[120:123]
	v_mfma_f32_16x16x32_bf16 v[108:111], v[148:151], v[202:205], v[108:111]
	v_mfma_f32_16x16x32_bf16 v[104:107], v[162:165], v[202:205], v[104:107]
	v_mfma_f32_16x16x32_bf16 v[92:95], v[148:151], v[214:217], v[92:95]
	v_mfma_f32_16x16x32_bf16 v[88:91], v[162:165], v[214:217], v[88:91]
	v_mfma_f32_16x16x32_bf16 v[76:79], v[148:151], v[222:225], v[76:79]
	v_mfma_f32_16x16x32_bf16 v[72:75], v[162:165], v[222:225], v[72:75]
	s_setprio 0
	s_setprio 1
	v_mfma_f32_16x16x32_bf16 v[116:119], v[166:169], v[182:185], v[116:119]
	v_mfma_f32_16x16x32_bf16 v[112:115], v[174:177], v[182:185], v[112:115]
	v_mfma_f32_16x16x32_bf16 v[100:103], v[166:169], v[198:201], v[100:103]
	v_mfma_f32_16x16x32_bf16 v[96:99], v[174:177], v[198:201], v[96:99]
	v_mfma_f32_16x16x32_bf16 v[84:87], v[166:169], v[210:213], v[84:87]
	v_mfma_f32_16x16x32_bf16 v[80:83], v[174:177], v[210:213], v[80:83]
	v_mfma_f32_16x16x32_bf16 v[68:71], v[166:169], v[218:221], v[68:71]
	v_mfma_f32_16x16x32_bf16 v[64:67], v[174:177], v[218:221], v[64:67]
	v_mfma_f32_16x16x32_bf16 v[116:119], v[170:173], v[194:197], v[116:119]
	v_mfma_f32_16x16x32_bf16 v[112:115], v[178:181], v[194:197], v[112:115]
	v_mfma_f32_16x16x32_bf16 v[100:103], v[170:173], v[202:205], v[100:103]
	v_mfma_f32_16x16x32_bf16 v[96:99], v[178:181], v[202:205], v[96:99]
	v_mfma_f32_16x16x32_bf16 v[84:87], v[170:173], v[214:217], v[84:87]
	v_mfma_f32_16x16x32_bf16 v[80:83], v[178:181], v[214:217], v[80:83]
	v_mfma_f32_16x16x32_bf16 v[68:71], v[170:173], v[222:225], v[68:71]
	v_mfma_f32_16x16x32_bf16 v[64:67], v[178:181], v[222:225], v[64:67]
	s_setprio 0
	s_barrier
	s_add_i32 s41, s41, s23
	s_mov_b32 m0, s41
	ds_read_b128 v[182:185], v161 offset:16384
	ds_read_b128 v[194:197], v161 offset:17408
	ds_read_b128 v[198:201], v161 offset:18432
	ds_read_b128 v[202:205], v161 offset:19456
	ds_read_b128 v[210:213], v161 offset:20480
	ds_read_b128 v[214:217], v161 offset:21504
	ds_read_b128 v[218:221], v161 offset:22528
	ds_read_b128 v[222:225], v161 offset:23552
	global_load_lds_dwordx4 v130, s[18:19]
	s_add_i32 m0, s41, 0x2000
	s_add_u32 s42, s18, 0x40000
	s_addc_u32 s43, s19, 0
	s_add_i32 s41, s44, s23
	global_load_lds_dwordx4 v134, s[18:19]
	s_mov_b32 m0, s41
	s_add_u32 s90, s20, 0x80
	s_addc_u32 s91, s21, 0
	global_load_lds_dwordx4 v130, s[42:43]
	s_add_i32 m0, s41, 0x2000
	s_nop 0
	global_load_lds_dwordx4 v134, s[42:43]
	s_mov_b32 m0, s24
	s_nop 0
	global_load_lds_dwordx4 v128, s[20:21]
	s_mov_b32 m0, s25
	s_nop 0
	global_load_lds_dwordx4 v132, s[20:21]
	s_waitcnt vmcnt(8)
	s_waitcnt lgkmcnt(0)
	s_barrier
	s_setprio 1
	s_waitcnt lgkmcnt(0)
	v_mfma_f32_16x16x32_bf16 v[60:63], v[144:147], v[182:185], v[60:63]
	v_mfma_f32_16x16x32_bf16 v[56:59], v[152:155], v[182:185], v[56:59]
	v_mfma_f32_16x16x32_bf16 v[44:47], v[144:147], v[198:201], v[44:47]
	v_mfma_f32_16x16x32_bf16 v[40:43], v[152:155], v[198:201], v[40:43]
	v_mfma_f32_16x16x32_bf16 v[28:31], v[144:147], v[210:213], v[28:31]
	v_mfma_f32_16x16x32_bf16 v[24:27], v[152:155], v[210:213], v[24:27]
	v_mfma_f32_16x16x32_bf16 v[12:15], v[144:147], v[218:221], v[12:15]
	v_mfma_f32_16x16x32_bf16 v[8:11], v[152:155], v[218:221], v[8:11]
	v_mfma_f32_16x16x32_bf16 v[60:63], v[148:151], v[194:197], v[60:63]
	v_mfma_f32_16x16x32_bf16 v[56:59], v[162:165], v[194:197], v[56:59]
	v_mfma_f32_16x16x32_bf16 v[44:47], v[148:151], v[202:205], v[44:47]
	v_mfma_f32_16x16x32_bf16 v[40:43], v[162:165], v[202:205], v[40:43]
	v_mfma_f32_16x16x32_bf16 v[28:31], v[148:151], v[214:217], v[28:31]
	v_mfma_f32_16x16x32_bf16 v[24:27], v[162:165], v[214:217], v[24:27]
	v_mfma_f32_16x16x32_bf16 v[12:15], v[148:151], v[222:225], v[12:15]
	v_mfma_f32_16x16x32_bf16 v[8:11], v[162:165], v[222:225], v[8:11]
	s_setprio 0
	s_setprio 1
	v_mfma_f32_16x16x32_bf16 v[52:55], v[166:169], v[182:185], v[52:55]
	v_mfma_f32_16x16x32_bf16 v[48:51], v[174:177], v[182:185], v[48:51]
	v_mfma_f32_16x16x32_bf16 v[36:39], v[166:169], v[198:201], v[36:39]
	v_mfma_f32_16x16x32_bf16 v[32:35], v[174:177], v[198:201], v[32:35]
	v_mfma_f32_16x16x32_bf16 v[20:23], v[166:169], v[210:213], v[20:23]
	v_mfma_f32_16x16x32_bf16 v[16:19], v[174:177], v[210:213], v[16:19]
	v_mfma_f32_16x16x32_bf16 v[4:7], v[166:169], v[218:221], v[4:7]
	v_mfma_f32_16x16x32_bf16 v[0:3], v[174:177], v[218:221], v[0:3]
	v_mfma_f32_16x16x32_bf16 v[52:55], v[170:173], v[194:197], v[52:55]
	v_mfma_f32_16x16x32_bf16 v[48:51], v[178:181], v[194:197], v[48:51]
	v_mfma_f32_16x16x32_bf16 v[36:39], v[170:173], v[202:205], v[36:39]
	v_mfma_f32_16x16x32_bf16 v[32:35], v[178:181], v[202:205], v[32:35]
	v_mfma_f32_16x16x32_bf16 v[20:23], v[170:173], v[214:217], v[20:23]
	v_mfma_f32_16x16x32_bf16 v[16:19], v[178:181], v[214:217], v[16:19]
	v_mfma_f32_16x16x32_bf16 v[4:7], v[170:173], v[222:225], v[4:7]
	v_mfma_f32_16x16x32_bf16 v[0:3], v[178:181], v[222:225], v[0:3]
	s_setprio 0
	s_barrier
; #define PG8_STAGE(bufoff, gbase, voff) do { _Pragma("unroll") for (int _i = 0; _i < 2; ++_i) \
;         __builtin_amdgcn_global_load_lds((const unsigned*)((const char*)(gbase) + (voff)[_i]), (PG8_LAS unsigned*)(lds + (bufoff) + ldsw + _i * 8192), 16, 0, 0); } while (0)
; #define PG8_LDA(dst, b, h) do { _Pragma("unroll") for (int m = 0; m < 4; ++m) _Pragma("unroll") for (int k = 0; k < 2; ++k) dst[m][k] = *(const PG8_LAS bf16x8*)(lds + PG8_SA(b, h) + aoff + m * 2048 + k * 1024); } while (0)
; #define PG8_LDB(dst, b, h) do { _Pragma("unroll") for (int n = 0; n < 2; ++n) _Pragma("unroll") for (int k = 0; k < 2; ++k) dst[n][k] = *(const PG8_LAS bf16x8*)(lds + PG8_SB(b, h) + boff + n * 2048 + k * 1024); } while (0)
; #define PG8_MMA(ai, bj, At, Bt) do { __builtin_amdgcn_s_setprio(1); _Pragma("unroll") for (int m = 0; m < 4; ++m) _Pragma("unroll") for (int n = 0; n < 2; ++n) _Pragma("unroll") for (int k = 0; k < 2; ++k) \
;         acc[ai][bj][m][n] = __builtin_amdgcn_mfma_f32_16x16x32_bf16(Bt[n][k], At[m][k], acc[ai][bj][m][n], 0, 0, 0); __builtin_amdgcn_s_setprio(0); } while (0)
; #define PG8_WAIT_V(n) asm volatile("s_waitcnt vmcnt(" #n ")" ::: "memory")
; #define PG8_WAIT_L(n) asm volatile("s_waitcnt lgkmcnt(" #n ")" ::: "memory")
; #define PG8_BAR __builtin_amdgcn_s_barrier()
; #define PG8_SCHED __builtin_amdgcn_sched_barrier(0)
; template <class Epi, class Sched, bool ALIGN_EPI = false, bool SP2 = false>
; __device__ __forceinline__ void gemm_phase(PG8_LAS unsigned char* lds, const Gemm g, const Sched& S, const Epi& E) {
;     ...
;         for (int t = 0; t < nt; t += 2) {
;             const bool last = (t == nt - 2);
;             const char* a1 = cA + (size_t)(t + 1) * kstep;
;             const char* a2 = last ? nA : cA + (size_t)(t + 2) * kstep; const char* b2 = last ? nB : cB + (size_t)(t + 2) * kstep;
;     ...
;             PG8_LDB(B0, 1, 0); PG8_LDB(B1, 1, 1); PG8_SCHED; PG8_LDA(At, 1, 0); PG8_STAGE(PG8_SA(0, 1), a2 + hstep, voffA);
;             PG8_WAIT_V(8); PG8_WAIT_L(0); PG8_BAR; PG8_MMA(0, 0, At, B0); PG8_MMA(0, 1, At, B1); PG8_BAR; PG8_SCHED;
;             PG8_LDA(At, 1, 1); PG8_STAGE(PG8_SB(1, 0), b3, voffB); PG8_STAGE(PG8_SB(1, 1), b3 + hstep, voffB); PG8_STAGE(PG8_SA(1, 0), a3, voffA);
;             PG8_WAIT_V(8); PG8_WAIT_L(0); PG8_BAR; PG8_MMA(1, 0, At, B0); PG8_MMA(1, 1, At, B1); PG8_BAR; PG8_SCHED;
	s_add_i32 s41, 0, 0x18000
	s_add_i32 s42, 0, 0x1c000
	v_add_u32_e32 v162, s41, v159
	v_add_u32_e32 v178, s42, v159
	ds_read_b128 v[144:147], v162
	ds_read_b128 v[148:151], v162 offset:1024
	ds_read_b128 v[152:155], v162 offset:2048
	ds_read_b128 v[162:165], v162 offset:3072
	ds_read_b128 v[166:169], v178
	ds_read_b128 v[170:173], v178 offset:1024
	ds_read_b128 v[174:177], v178 offset:2048
	ds_read_b128 v[178:181], v178 offset:3072
	s_add_u32 s20, s20, 0x40000
	s_addc_u32 s21, s21, 0
	s_mov_b32 m0, s26
	ds_read_b128 v[182:185], v161 offset:32768
	ds_read_b128 v[194:197], v161 offset:33792
	ds_read_b128 v[198:201], v161 offset:34816
	ds_read_b128 v[202:205], v161 offset:35840
	ds_read_b128 v[210:213], v161 offset:36864
	ds_read_b128 v[214:217], v161 offset:37888
	ds_read_b128 v[218:221], v161 offset:38912
	ds_read_b128 v[222:225], v161 offset:39936
	global_load_lds_dwordx4 v128, s[20:21]
	s_mov_b32 m0, s27
	s_nop 0
	global_load_lds_dwordx4 v132, s[20:21]
	s_waitcnt vmcnt(8)
	s_waitcnt lgkmcnt(0)
	s_barrier
	s_setprio 1
	s_waitcnt lgkmcnt(0)
	v_mfma_f32_16x16x32_bf16 v[124:127], v[144:147], v[182:185], v[124:127]
	v_mfma_f32_16x16x32_bf16 v[120:123], v[152:155], v[182:185], v[120:123]
	v_mfma_f32_16x16x32_bf16 v[108:111], v[144:147], v[198:201], v[108:111]
	v_mfma_f32_16x16x32_bf16 v[104:107], v[152:155], v[198:201], v[104:107]
	v_mfma_f32_16x16x32_bf16 v[92:95], v[144:147], v[210:213], v[92:95]
	v_mfma_f32_16x16x32_bf16 v[88:91], v[152:155], v[210:213], v[88:91]
	v_mfma_f32_16x16x32_bf16 v[76:79], v[144:147], v[218:221], v[76:79]
	v_mfma_f32_16x16x32_bf16 v[72:75], v[152:155], v[218:221], v[72:75]
	v_mfma_f32_16x16x32_bf16 v[124:127], v[148:151], v[194:197], v[124:127]
	v_mfma_f32_16x16x32_bf16 v[120:123], v[162:165], v[194:197], v[120:123]
	v_mfma_f32_16x16x32_bf16 v[108:111], v[148:151], v[202:205], v[108:111]
	v_mfma_f32_16x16x32_bf16 v[104:107], v[162:165], v[202:205], v[104:107]
	v_mfma_f32_16x16x32_bf16 v[92:95], v[148:151], v[214:217], v[92:95]
	v_mfma_f32_16x16x32_bf16 v[88:91], v[162:165], v[214:217], v[88:91]
	v_mfma_f32_16x16x32_bf16 v[76:79], v[148:151], v[222:225], v[76:79]
	v_mfma_f32_16x16x32_bf16 v[72:75], v[162:165], v[222:225], v[72:75]
	s_setprio 0
	s_setprio 1
	v_mfma_f32_16x16x32_bf16 v[116:119], v[166:169], v[182:185], v[116:119]
	v_mfma_f32_16x16x32_bf16 v[112:115], v[174:177], v[182:185], v[112:115]
	v_mfma_f32_16x16x32_bf16 v[100:103], v[166:169], v[198:201], v[100:103]
	v_mfma_f32_16x16x32_bf16 v[96:99], v[174:177], v[198:201], v[96:99]
	v_mfma_f32_16x16x32_bf16 v[84:87], v[166:169], v[210:213], v[84:87]
	v_mfma_f32_16x16x32_bf16 v[80:83], v[174:177], v[210:213], v[80:83]
	v_mfma_f32_16x16x32_bf16 v[68:71], v[166:169], v[218:221], v[68:71]
	v_mfma_f32_16x16x32_bf16 v[64:67], v[174:177], v[218:221], v[64:67]
	v_mfma_f32_16x16x32_bf16 v[116:119], v[170:173], v[194:197], v[116:119]
	v_mfma_f32_16x16x32_bf16 v[112:115], v[178:181], v[194:197], v[112:115]
	v_mfma_f32_16x16x32_bf16 v[100:103], v[170:173], v[202:205], v[100:103]
	v_mfma_f32_16x16x32_bf16 v[96:99], v[178:181], v[202:205], v[96:99]
	v_mfma_f32_16x16x32_bf16 v[84:87], v[170:173], v[214:217], v[84:87]
	v_mfma_f32_16x16x32_bf16 v[80:83], v[178:181], v[214:217], v[80:83]
	v_mfma_f32_16x16x32_bf16 v[68:71], v[170:173], v[222:225], v[68:71]
	v_mfma_f32_16x16x32_bf16 v[64:67], v[178:181], v[222:225], v[64:67]
	s_setprio 0
	s_barrier
	s_add_i32 s20, s41, s23
	s_add_u32 s92, s18, 0x80
	s_addc_u32 s93, s19, 0
	s_mov_b32 m0, s20
	ds_read_b128 v[182:185], v161 offset:49152
	ds_read_b128 v[194:197], v161 offset:50176
	ds_read_b128 v[198:201], v161 offset:51200
	ds_read_b128 v[202:205], v161 offset:52224
	ds_read_b128 v[210:213], v161 offset:53248
	ds_read_b128 v[214:217], v161 offset:54272
	ds_read_b128 v[218:221], v161 offset:55296
	ds_read_b128 v[222:225], v161 offset:56320
	global_load_lds_dwordx4 v130, s[92:93]
	s_add_i32 m0, s20, 0x2000
	s_add_i32 s20, s42, s23
	global_load_lds_dwordx4 v134, s[92:93]
	s_add_u32 s18, s18, 0x40080
	s_addc_u32 s19, s19, 0
	s_mov_b32 m0, s20
	s_nop 0
	global_load_lds_dwordx4 v130, s[18:19]
	s_add_i32 m0, s20, 0x2000
	s_nop 0
	global_load_lds_dwordx4 v134, s[18:19]
	s_mov_b32 m0, s30
	s_nop 0
	global_load_lds_dwordx4 v128, s[90:91]
	s_mov_b32 m0, s31
	s_nop 0
	global_load_lds_dwordx4 v132, s[90:91]
	s_waitcnt vmcnt(8)
	s_waitcnt lgkmcnt(0)
	s_barrier
	s_setprio 1
	s_waitcnt lgkmcnt(0)
	v_mfma_f32_16x16x32_bf16 v[60:63], v[144:147], v[182:185], v[60:63]
	v_mfma_f32_16x16x32_bf16 v[56:59], v[152:155], v[182:185], v[56:59]
	v_mfma_f32_16x16x32_bf16 v[44:47], v[144:147], v[198:201], v[44:47]
	v_mfma_f32_16x16x32_bf16 v[40:43], v[152:155], v[198:201], v[40:43]
	v_mfma_f32_16x16x32_bf16 v[28:31], v[144:147], v[210:213], v[28:31]
	v_mfma_f32_16x16x32_bf16 v[24:27], v[152:155], v[210:213], v[24:27]
	v_mfma_f32_16x16x32_bf16 v[12:15], v[144:147], v[218:221], v[12:15]
	v_mfma_f32_16x16x32_bf16 v[8:11], v[152:155], v[218:221], v[8:11]
	v_mfma_f32_16x16x32_bf16 v[60:63], v[148:151], v[194:197], v[60:63]
	v_mfma_f32_16x16x32_bf16 v[56:59], v[162:165], v[194:197], v[56:59]
	v_mfma_f32_16x16x32_bf16 v[44:47], v[148:151], v[202:205], v[44:47]
	v_mfma_f32_16x16x32_bf16 v[40:43], v[162:165], v[202:205], v[40:43]
	v_mfma_f32_16x16x32_bf16 v[28:31], v[148:151], v[214:217], v[28:31]
	v_mfma_f32_16x16x32_bf16 v[24:27], v[162:165], v[214:217], v[24:27]
	v_mfma_f32_16x16x32_bf16 v[12:15], v[148:151], v[222:225], v[12:15]
	v_mfma_f32_16x16x32_bf16 v[8:11], v[162:165], v[222:225], v[8:11]
	s_setprio 0
	s_setprio 1
	v_mfma_f32_16x16x32_bf16 v[52:55], v[166:169], v[182:185], v[52:55]
	v_mfma_f32_16x16x32_bf16 v[48:51], v[174:177], v[182:185], v[48:51]
	v_mfma_f32_16x16x32_bf16 v[36:39], v[166:169], v[198:201], v[36:39]
	v_mfma_f32_16x16x32_bf16 v[32:35], v[174:177], v[198:201], v[32:35]
	v_mfma_f32_16x16x32_bf16 v[20:23], v[166:169], v[210:213], v[20:23]
	v_mfma_f32_16x16x32_bf16 v[16:19], v[174:177], v[210:213], v[16:19]
	v_mfma_f32_16x16x32_bf16 v[4:7], v[166:169], v[218:221], v[4:7]
	v_mfma_f32_16x16x32_bf16 v[0:3], v[174:177], v[218:221], v[0:3]
	v_mfma_f32_16x16x32_bf16 v[52:55], v[170:173], v[194:197], v[52:55]
	v_mfma_f32_16x16x32_bf16 v[48:51], v[178:181], v[194:197], v[48:51]
	v_mfma_f32_16x16x32_bf16 v[36:39], v[170:173], v[202:205], v[36:39]
	v_mfma_f32_16x16x32_bf16 v[32:35], v[178:181], v[202:205], v[32:35]
	v_mfma_f32_16x16x32_bf16 v[20:23], v[170:173], v[214:217], v[20:23]
	v_mfma_f32_16x16x32_bf16 v[16:19], v[178:181], v[214:217], v[16:19]
	v_mfma_f32_16x16x32_bf16 v[4:7], v[170:173], v[222:225], v[4:7]
	v_mfma_f32_16x16x32_bf16 v[0:3], v[178:181], v[222:225], v[0:3]
	s_setprio 0
	s_barrier
	s_add_i32 s40, s40, 2
	s_add_u32 s16, s16, 0x100
	s_addc_u32 s17, s17, 0
	s_add_u32 s38, s38, 0x100
	s_addc_u32 s39, s39, 0
	s_cmp_gt_u32 s40, 13
	s_cbranch_scc0 .LBB0_133
	s_and_b64 vcc, exec, s[6:7]
	s_cbranch_vccz .LBB0_136
	s_barrier
